# P5 K-loop: LDS-DMA pieces balanced 4/4/4/4 per load segment (As[b][0] restage moved to next SP1 segment)
# speedup vs baseline: 1.0037x; 1.0001x over previous
; #define PG8_STAGE(bufoff, gbase, voff) do { _Pragma("unroll") for (int _i = 0; _i < 2; ++_i) \
;         __builtin_amdgcn_global_load_lds((const unsigned*)((const char*)(gbase) + (voff)[_i]), (PG8_LAS unsigned*)(lds + (bufoff) + ldsw + _i * 8192), 16, 0, 0); } while (0)
; #define PG8_WAIT_V(n) asm volatile("s_waitcnt vmcnt(" #n ")" ::: "memory")
; #define PG8_BAR __builtin_amdgcn_s_barrier()
; template <class Epi, class Sched, bool ALIGN_EPI = false, bool SP2 = false>
; __device__ __forceinline__ void gemm_phase(PG8_LAS unsigned char* lds, const Gemm g, const Sched& S, const Epi& E) {
;     ...
;         PG8_STAGE(PG8_SB(0, 0), cB, voffB); PG8_STAGE(PG8_SB(0, 1), cB + hstep, voffB); PG8_STAGE(PG8_SA(0, 0), cA, voffA); PG8_STAGE(PG8_SA(0, 1), cA + hstep, voffA);
;         if (wr == 1) PG8_BAR;
;         PG8_WAIT_V(2); PG8_BAR;
;         PG8_STAGE(PG8_SB(1, 0), cB + kstep, voffB); PG8_STAGE(PG8_SA(1, 0), cA + kstep, voffA); PG8_STAGE(PG8_SB(1, 1), cB + hstep + kstep, voffB);
;         PG8_WAIT_V(6); PG8_BAR;
.LBB0_734:
	s_lshl_b32 s12, s2, 11
	s_lshl_b32 s1, s1, 5
	s_and_b32 s60, s12, 0x3800
	s_mov_b64 s[12:13], 0x80
	s_and_b32 s1, s1, 0x60
	s_add_i32 m0, s48, 0x18000
	v_lshl_add_u64 v[10:11], v[10:11], 0, s[12:13]
	s_lshl_b32 s16, s0, 13
	s_lshl_b32 s17, s1, 7
	s_waitcnt vmcnt(2)
	s_barrier
	global_load_lds_dwordx4 v[10:11], off
	v_lshl_add_u64 v[8:9], v[8:9], 0, s[12:13]
	s_add_i32 m0, s48, 0x1a000
	s_add_i32 s61, s48, 0x8000
	s_add_i32 s62, s48, 0xa000
	global_load_lds_dwordx4 v[8:9], off
	s_add_u32 s14, s40, 0x40080
	s_addc_u32 s15, s41, 0
	s_add_i32 m0, s48, 0x1c000
	v_lshl_add_u64 v[4:5], s[14:15], 0, v[132:133]
	global_load_lds_dwordx4 v[4:5], off
	v_lshl_add_u64 v[4:5], s[14:15], 0, v[136:137]
	s_add_i32 m0, s48, 0x1e000
	v_lshlrev_b32_e32 v6, 2, v0
	global_load_lds_dwordx4 v[4:5], off
	v_and_b32_e32 v4, 15, v0
	v_lshlrev_b32_e32 v5, 1, v2
	v_lshl_or_b32 v1, s0, 6, v4
	v_lshl_or_b32 v4, v4, 6, v5
	v_and_b32_e32 v6, 32, v6
	s_movk_i32 s0, 0x3c0
	v_bitop3_b32 v4, v4, s16, v6 bitop3:0xde
	v_and_or_b32 v5, v13, s0, v5
	v_and_b32_e32 v6, 32, v12
	v_bitop3_b32 v151, s17, v5, v6 bitop3:0xf6
	v_lshlrev_b32_e32 v5, 8, v0
	v_and_b32_e32 v5, 0x18000, v5
	v_lshlrev_b32_e32 v6, 11, v15
	v_or3_b32 v5, v3, v5, v6
	v_add_u32_e32 v140, v5, v14
	v_lshlrev_b32_e32 v5, 4, v16
	s_waitcnt vmcnt(4)
	s_cmpk_lt_u32 s4, 0x100
	v_and_b32_e32 v5, 0x38000, v5
	s_cselect_b64 s[14:15], -1, 0
	v_or3_b32 v3, v3, v5, v6
	s_add_i32 s66, 0, 0x10000
	s_add_i32 s67, 0, 0x14000
	s_ashr_i32 s63, s3, 31
	s_ashr_i32 s64, s2, 31
	v_mov_b32_e32 v141, v139
	v_add_u32_e32 v142, v3, v14
	v_mov_b32_e32 v143, v139
	v_mov_b64_e32 v[144:145], 0x580
	v_mov_b64_e32 v[146:147], 0x57f
	s_movk_i32 s65, 0xb1
	v_add_u32_e32 v152, s66, v151
	v_add_u32_e32 v153, s67, v151
	v_add_u32_e32 v154, 0, v4
	v_mov_b32_e32 v155, 0x358637bd
	s_movk_i32 s68, 0x1600
	s_lshl_b32 s4, s1, 1
	v_lshlrev_b32_e32 v138, 1, v2
	s_mov_b32 s69, s5
	s_barrier
	s_branch .LBB0_737

; #define PG8_STAGE(bufoff, gbase, voff) do { _Pragma("unroll") for (int _i = 0; _i < 2; ++_i) \
;         __builtin_amdgcn_global_load_lds((const unsigned*)((const char*)(gbase) + (voff)[_i]), (PG8_LAS unsigned*)(lds + (bufoff) + ldsw + _i * 8192), 16, 0, 0); } while (0)
; #define PG8_LDA(dst, b, h) do { _Pragma("unroll") for (int m = 0; m < 4; ++m) _Pragma("unroll") for (int k = 0; k < 2; ++k) dst[m][k] = *(const PG8_LAS bf16x8*)(lds + PG8_SA(b, h) + aoff + m * 2048 + k * 1024); } while (0)
; #define PG8_LDB(dst, b, h) do { _Pragma("unroll") for (int n = 0; n < 2; ++n) _Pragma("unroll") for (int k = 0; k < 2; ++k) dst[n][k] = *(const PG8_LAS bf16x8*)(lds + PG8_SB(b, h) + boff + n * 2048 + k * 1024); } while (0)
; #define PG8_MMA(ai, bj, At, Bt) do { __builtin_amdgcn_s_setprio(1); _Pragma("unroll") for (int m = 0; m < 4; ++m) _Pragma("unroll") for (int n = 0; n < 2; ++n) _Pragma("unroll") for (int k = 0; k < 2; ++k) \
;         acc[ai][bj][m][n] = __builtin_amdgcn_mfma_f32_16x16x32_bf16(Bt[n][k], At[m][k], acc[ai][bj][m][n], 0, 0, 0); __builtin_amdgcn_s_setprio(0); } while (0)
; #define PG8_WAIT_V(n) asm volatile("s_waitcnt vmcnt(" #n ")" ::: "memory")
; #define PG8_WAIT_L(n) asm volatile("s_waitcnt lgkmcnt(" #n ")" ::: "memory")
; #define PG8_BAR __builtin_amdgcn_s_barrier()
; #define PG8_SCHED __builtin_amdgcn_sched_barrier(0)
; template <class Epi, class Sched, bool ALIGN_EPI = false, bool SP2 = false>
; __device__ __forceinline__ void gemm_phase(PG8_LAS unsigned char* lds, const Gemm g, const Sched& S, const Epi& E) {
;     ...
;             PG8_LDB(B0, 0, 0); PG8_LDB(B1, 0, 1); PG8_SCHED; PG8_LDA(At, 0, 0); PG8_STAGE(PG8_SA(1, 1), a1 + hstep, voffA);
;             PG8_WAIT_V(8); PG8_WAIT_L(0); PG8_BAR; PG8_MMA(0, 0, At, B0); PG8_MMA(0, 1, At, B1); PG8_BAR; PG8_SCHED;
;             PG8_LDA(At, 0, 1); PG8_STAGE(PG8_SB(0, 0), b2, voffB); PG8_STAGE(PG8_SB(0, 1), b2 + hstep, voffB); PG8_STAGE(PG8_SA(0, 0), a2, voffA);
.LBB0_740:
	ds_read_b128 v[156:159], v152
	ds_read_b128 v[160:163], v152 offset:1024
	ds_read_b128 v[164:167], v152 offset:2048
	ds_read_b128 v[168:171], v152 offset:3072
	ds_read_b128 v[172:175], v153
	ds_read_b128 v[176:179], v153 offset:1024
	ds_read_b128 v[180:183], v153 offset:2048
	ds_read_b128 v[184:187], v153 offset:3072
	s_add_u32 s40, s30, 0xfffc0080
	s_addc_u32 s41, s31, -1
	s_cmp_eq_u32 s71, 12
	s_cselect_b32 s45, s19, s41
	s_cselect_b32 s44, s25, s40
	s_cselect_b32 s41, s17, s70
	s_cselect_b32 s40, s27, s33
	s_add_u32 s98, s30, 0xfffc0000
	s_addc_u32 s99, s31, -1
	v_lshl_add_u64 v[148:149], s[30:31], 0, v[140:141]
	s_mov_b32 m0, s61
	ds_read_b128 v[188:191], v154
	ds_read_b128 v[192:195], v154 offset:1024
	ds_read_b128 v[196:199], v154 offset:2048
	ds_read_b128 v[200:203], v154 offset:3072
	ds_read_b128 v[208:211], v154 offset:4096
	ds_read_b128 v[212:215], v154 offset:5120
	ds_read_b128 v[216:219], v154 offset:6144
	ds_read_b128 v[220:223], v154 offset:7168
	global_load_lds_dwordx4 v130, s[98:99]
	s_mov_b32 m0, s62
	s_nop 0
	global_load_lds_dwordx4 v134, s[98:99]
	s_add_i32 m0, s48, 0xc000
	s_nop 0
	global_load_lds_dwordx4 v[148:149], off
	v_lshl_add_u64 v[148:149], s[30:31], 0, v[142:143]
	s_add_i32 m0, s48, 0xe000
	s_nop 0
	global_load_lds_dwordx4 v[148:149], off
	s_waitcnt vmcnt(8)
	s_waitcnt lgkmcnt(0)
	s_barrier
	s_setprio 1
	s_waitcnt lgkmcnt(0)
	v_mfma_f32_16x16x32_bf16 v[126:129], v[156:159], v[188:191], v[126:129]
	v_mfma_f32_16x16x32_bf16 v[122:125], v[164:167], v[188:191], v[122:125]
	v_mfma_f32_16x16x32_bf16 v[110:113], v[156:159], v[196:199], v[110:113]
	v_mfma_f32_16x16x32_bf16 v[106:109], v[164:167], v[196:199], v[106:109]
	v_mfma_f32_16x16x32_bf16 v[94:97], v[156:159], v[208:211], v[94:97]
	v_mfma_f32_16x16x32_bf16 v[90:93], v[164:167], v[208:211], v[90:93]
	v_mfma_f32_16x16x32_bf16 v[78:81], v[156:159], v[216:219], v[78:81]
	v_mfma_f32_16x16x32_bf16 v[74:77], v[164:167], v[216:219], v[74:77]
	v_mfma_f32_16x16x32_bf16 v[126:129], v[160:163], v[192:195], v[126:129]
	v_mfma_f32_16x16x32_bf16 v[122:125], v[168:171], v[192:195], v[122:125]
	v_mfma_f32_16x16x32_bf16 v[110:113], v[160:163], v[200:203], v[110:113]
	v_mfma_f32_16x16x32_bf16 v[106:109], v[168:171], v[200:203], v[106:109]
	v_mfma_f32_16x16x32_bf16 v[94:97], v[160:163], v[212:215], v[94:97]
	v_mfma_f32_16x16x32_bf16 v[90:93], v[168:171], v[212:215], v[90:93]
	v_mfma_f32_16x16x32_bf16 v[78:81], v[160:163], v[220:223], v[78:81]
	v_mfma_f32_16x16x32_bf16 v[74:77], v[168:171], v[220:223], v[74:77]
	s_setprio 0
	s_setprio 1
	v_mfma_f32_16x16x32_bf16 v[118:121], v[172:175], v[188:191], v[118:121]
	v_mfma_f32_16x16x32_bf16 v[114:117], v[180:183], v[188:191], v[114:117]
	v_mfma_f32_16x16x32_bf16 v[102:105], v[172:175], v[196:199], v[102:105]
	v_mfma_f32_16x16x32_bf16 v[98:101], v[180:183], v[196:199], v[98:101]
	v_mfma_f32_16x16x32_bf16 v[86:89], v[172:175], v[208:211], v[86:89]
	v_mfma_f32_16x16x32_bf16 v[82:85], v[180:183], v[208:211], v[82:85]
	v_mfma_f32_16x16x32_bf16 v[70:73], v[172:175], v[216:219], v[70:73]
	v_mfma_f32_16x16x32_bf16 v[66:69], v[180:183], v[216:219], v[66:69]
	v_mfma_f32_16x16x32_bf16 v[118:121], v[176:179], v[192:195], v[118:121]
	v_mfma_f32_16x16x32_bf16 v[114:117], v[184:187], v[192:195], v[114:117]
	v_mfma_f32_16x16x32_bf16 v[102:105], v[176:179], v[200:203], v[102:105]
	v_mfma_f32_16x16x32_bf16 v[98:101], v[184:187], v[200:203], v[98:101]
	v_mfma_f32_16x16x32_bf16 v[86:89], v[176:179], v[212:215], v[86:89]
	v_mfma_f32_16x16x32_bf16 v[82:85], v[184:187], v[212:215], v[82:85]
	v_mfma_f32_16x16x32_bf16 v[70:73], v[176:179], v[220:223], v[70:73]
	v_mfma_f32_16x16x32_bf16 v[66:69], v[184:187], v[220:223], v[66:69]
	s_setprio 0
	s_barrier
	s_add_i32 s72, s66, s47
	s_mov_b32 m0, s72
	ds_read_b128 v[188:191], v154 offset:16384
	ds_read_b128 v[192:195], v154 offset:17408
	ds_read_b128 v[196:199], v154 offset:18432
	ds_read_b128 v[200:203], v154 offset:19456
	ds_read_b128 v[208:211], v154 offset:20480
	ds_read_b128 v[212:215], v154 offset:21504
	ds_read_b128 v[216:219], v154 offset:22528
	ds_read_b128 v[220:223], v154 offset:23552
	global_load_lds_dwordx4 v132, s[40:41]
	s_add_i32 m0, s72, 0x2000
	s_add_u32 s72, s40, 0x40000
	v_lshl_add_u64 v[204:205], s[40:41], 0, v[136:137]
	s_addc_u32 s73, s41, 0
	s_add_i32 s74, s67, s47
	global_load_lds_dwordx4 v136, s[40:41]
	s_mov_b32 m0, s74
	s_nop 0
	global_load_lds_dwordx4 v132, s[72:73]
	s_add_i32 m0, s74, 0x2000
	s_nop 0
	global_load_lds_dwordx4 v136, s[72:73]
	s_waitcnt vmcnt(6)
	s_waitcnt lgkmcnt(0)
	s_barrier
; #define PG8_STAGE(bufoff, gbase, voff) do { _Pragma("unroll") for (int _i = 0; _i < 2; ++_i) \
;         __builtin_amdgcn_global_load_lds((const unsigned*)((const char*)(gbase) + (voff)[_i]), (PG8_LAS unsigned*)(lds + (bufoff) + ldsw + _i * 8192), 16, 0, 0); } while (0)
; #define PG8_LDA(dst, b, h) do { _Pragma("unroll") for (int m = 0; m < 4; ++m) _Pragma("unroll") for (int k = 0; k < 2; ++k) dst[m][k] = *(const PG8_LAS bf16x8*)(lds + PG8_SA(b, h) + aoff + m * 2048 + k * 1024); } while (0)
; #define PG8_LDB(dst, b, h) do { _Pragma("unroll") for (int n = 0; n < 2; ++n) _Pragma("unroll") for (int k = 0; k < 2; ++k) dst[n][k] = *(const PG8_LAS bf16x8*)(lds + PG8_SB(b, h) + boff + n * 2048 + k * 1024); } while (0)
; #define PG8_MMA(ai, bj, At, Bt) do { __builtin_amdgcn_s_setprio(1); _Pragma("unroll") for (int m = 0; m < 4; ++m) _Pragma("unroll") for (int n = 0; n < 2; ++n) _Pragma("unroll") for (int k = 0; k < 2; ++k) \
;         acc[ai][bj][m][n] = __builtin_amdgcn_mfma_f32_16x16x32_bf16(Bt[n][k], At[m][k], acc[ai][bj][m][n], 0, 0, 0); __builtin_amdgcn_s_setprio(0); } while (0)
; #define PG8_WAIT_V(n) asm volatile("s_waitcnt vmcnt(" #n ")" ::: "memory")
; #define PG8_WAIT_L(n) asm volatile("s_waitcnt lgkmcnt(" #n ")" ::: "memory")
; #define PG8_BAR __builtin_amdgcn_s_barrier()
; #define PG8_SCHED __builtin_amdgcn_sched_barrier(0)
; template <class Epi, class Sched, bool ALIGN_EPI = false, bool SP2 = false>
; __device__ __forceinline__ void gemm_phase(PG8_LAS unsigned char* lds, const Gemm g, const Sched& S, const Epi& E) {
;     ...
;             PG8_WAIT_V(8); PG8_WAIT_L(0); PG8_BAR; PG8_MMA(1, 0, At, B0); PG8_MMA(1, 1, At, B1); PG8_BAR; PG8_SCHED;
;             PG8_LDB(B0, 1, 0); PG8_LDB(B1, 1, 1); PG8_SCHED; PG8_LDA(At, 1, 0); PG8_STAGE(PG8_SA(0, 1), a2 + hstep, voffA);
	s_setprio 1
	s_waitcnt lgkmcnt(0)
	v_mfma_f32_16x16x32_bf16 v[62:65], v[156:159], v[188:191], v[62:65]
	v_mfma_f32_16x16x32_bf16 v[58:61], v[164:167], v[188:191], v[58:61]
	v_mfma_f32_16x16x32_bf16 v[46:49], v[156:159], v[196:199], v[46:49]
	v_mfma_f32_16x16x32_bf16 v[42:45], v[164:167], v[196:199], v[42:45]
	v_mfma_f32_16x16x32_bf16 v[30:33], v[156:159], v[208:211], v[30:33]
	v_mfma_f32_16x16x32_bf16 v[26:29], v[164:167], v[208:211], v[26:29]
	v_mfma_f32_16x16x32_bf16 v[14:17], v[156:159], v[216:219], v[14:17]
	v_mfma_f32_16x16x32_bf16 v[10:13], v[164:167], v[216:219], v[10:13]
	v_mfma_f32_16x16x32_bf16 v[62:65], v[160:163], v[192:195], v[62:65]
	v_mfma_f32_16x16x32_bf16 v[58:61], v[168:171], v[192:195], v[58:61]
	v_mfma_f32_16x16x32_bf16 v[46:49], v[160:163], v[200:203], v[46:49]
	v_mfma_f32_16x16x32_bf16 v[42:45], v[168:171], v[200:203], v[42:45]
	v_mfma_f32_16x16x32_bf16 v[30:33], v[160:163], v[212:215], v[30:33]
	v_mfma_f32_16x16x32_bf16 v[26:29], v[168:171], v[212:215], v[26:29]
	v_mfma_f32_16x16x32_bf16 v[14:17], v[160:163], v[220:223], v[14:17]
	v_mfma_f32_16x16x32_bf16 v[10:13], v[168:171], v[220:223], v[10:13]
	s_setprio 0
	s_setprio 1
	v_mfma_f32_16x16x32_bf16 v[54:57], v[172:175], v[188:191], v[54:57]
	v_mfma_f32_16x16x32_bf16 v[50:53], v[180:183], v[188:191], v[50:53]
	v_mfma_f32_16x16x32_bf16 v[38:41], v[172:175], v[196:199], v[38:41]
	v_mfma_f32_16x16x32_bf16 v[34:37], v[180:183], v[196:199], v[34:37]
	v_mfma_f32_16x16x32_bf16 v[22:25], v[172:175], v[208:211], v[22:25]
	v_mfma_f32_16x16x32_bf16 v[18:21], v[180:183], v[208:211], v[18:21]
	v_mfma_f32_16x16x32_bf16 v[6:9], v[172:175], v[216:219], v[6:9]
	v_mfma_f32_16x16x32_bf16 v[2:5], v[180:183], v[216:219], v[2:5]
	v_mfma_f32_16x16x32_bf16 v[54:57], v[176:179], v[192:195], v[54:57]
	v_mfma_f32_16x16x32_bf16 v[50:53], v[184:187], v[192:195], v[50:53]
	v_mfma_f32_16x16x32_bf16 v[38:41], v[176:179], v[200:203], v[38:41]
	v_mfma_f32_16x16x32_bf16 v[34:37], v[184:187], v[200:203], v[34:37]
	v_mfma_f32_16x16x32_bf16 v[22:25], v[176:179], v[212:215], v[22:25]
	v_mfma_f32_16x16x32_bf16 v[18:21], v[184:187], v[212:215], v[18:21]
	v_mfma_f32_16x16x32_bf16 v[6:9], v[176:179], v[220:223], v[6:9]
	v_mfma_f32_16x16x32_bf16 v[2:5], v[184:187], v[220:223], v[2:5]
	s_setprio 0
	s_barrier
	s_add_i32 s72, 0, 0x18000
	v_add_u32_e32 v150, s72, v151
	s_add_i32 s73, 0, 0x1c000
	ds_read_b128 v[156:159], v150
	ds_read_b128 v[160:163], v150 offset:1024
	ds_read_b128 v[164:167], v150 offset:2048
	ds_read_b128 v[168:171], v150 offset:3072
	v_add_u32_e32 v150, s73, v151
	ds_read_b128 v[172:175], v150
	ds_read_b128 v[176:179], v150 offset:1024
	ds_read_b128 v[180:183], v150 offset:2048
	ds_read_b128 v[184:187], v150 offset:3072
	s_mov_b32 m0, s48
	ds_read_b128 v[188:191], v154 offset:32768
	ds_read_b128 v[192:195], v154 offset:33792
	ds_read_b128 v[196:199], v154 offset:34816
	ds_read_b128 v[200:203], v154 offset:35840
	ds_read_b128 v[208:211], v154 offset:36864
	ds_read_b128 v[212:215], v154 offset:37888
	ds_read_b128 v[216:219], v154 offset:38912
	ds_read_b128 v[220:223], v154 offset:39936
	global_load_lds_dwordx4 v130, s[44:45]
	s_mov_b32 m0, s49
	s_nop 0
	global_load_lds_dwordx4 v134, s[44:45]
	s_add_u32 s44, s44, 0x40000
	s_addc_u32 s45, s45, 0
	s_mov_b32 m0, s50
	s_nop 0
	global_load_lds_dwordx4 v130, s[44:45]
	s_mov_b32 m0, s51
	s_nop 0
	global_load_lds_dwordx4 v134, s[44:45]
	s_waitcnt vmcnt(8)
	s_waitcnt lgkmcnt(0)
	s_barrier
; #define PG8_STAGE(bufoff, gbase, voff) do { _Pragma("unroll") for (int _i = 0; _i < 2; ++_i) \
;         __builtin_amdgcn_global_load_lds((const unsigned*)((const char*)(gbase) + (voff)[_i]), (PG8_LAS unsigned*)(lds + (bufoff) + ldsw + _i * 8192), 16, 0, 0); } while (0)
; #define PG8_LDA(dst, b, h) do { _Pragma("unroll") for (int m = 0; m < 4; ++m) _Pragma("unroll") for (int k = 0; k < 2; ++k) dst[m][k] = *(const PG8_LAS bf16x8*)(lds + PG8_SA(b, h) + aoff + m * 2048 + k * 1024); } while (0)
; #define PG8_MMA(ai, bj, At, Bt) do { __builtin_amdgcn_s_setprio(1); _Pragma("unroll") for (int m = 0; m < 4; ++m) _Pragma("unroll") for (int n = 0; n < 2; ++n) _Pragma("unroll") for (int k = 0; k < 2; ++k) \
;         acc[ai][bj][m][n] = __builtin_amdgcn_mfma_f32_16x16x32_bf16(Bt[n][k], At[m][k], acc[ai][bj][m][n], 0, 0, 0); __builtin_amdgcn_s_setprio(0); } while (0)
; #define PG8_WAIT_V(n) asm volatile("s_waitcnt vmcnt(" #n ")" ::: "memory")
; #define PG8_WAIT_L(n) asm volatile("s_waitcnt lgkmcnt(" #n ")" ::: "memory")
; #define PG8_BAR __builtin_amdgcn_s_barrier()
; #define PG8_SCHED __builtin_amdgcn_sched_barrier(0)
; template <class Epi, class Sched, bool ALIGN_EPI = false, bool SP2 = false>
; __device__ __forceinline__ void gemm_phase(PG8_LAS unsigned char* lds, const Gemm g, const Sched& S, const Epi& E) {
;     ...
;             PG8_WAIT_V(8); PG8_WAIT_L(0); PG8_BAR; PG8_MMA(0, 0, At, B0); PG8_MMA(0, 1, At, B1); PG8_BAR; PG8_SCHED;
;             PG8_LDA(At, 1, 1); PG8_STAGE(PG8_SB(1, 0), b3, voffB); PG8_STAGE(PG8_SB(1, 1), b3 + hstep, voffB); PG8_STAGE(PG8_SA(1, 0), a3, voffA);
;             PG8_WAIT_V(8); PG8_WAIT_L(0); PG8_BAR; PG8_MMA(1, 0, At, B0); PG8_MMA(1, 1, At, B1); PG8_BAR; PG8_SCHED;
	s_setprio 1
	s_waitcnt lgkmcnt(0)
	v_mfma_f32_16x16x32_bf16 v[126:129], v[156:159], v[188:191], v[126:129]
	v_mfma_f32_16x16x32_bf16 v[122:125], v[164:167], v[188:191], v[122:125]
	v_mfma_f32_16x16x32_bf16 v[110:113], v[156:159], v[196:199], v[110:113]
	v_mfma_f32_16x16x32_bf16 v[106:109], v[164:167], v[196:199], v[106:109]
	v_mfma_f32_16x16x32_bf16 v[94:97], v[156:159], v[208:211], v[94:97]
	v_mfma_f32_16x16x32_bf16 v[90:93], v[164:167], v[208:211], v[90:93]
	v_mfma_f32_16x16x32_bf16 v[78:81], v[156:159], v[216:219], v[78:81]
	v_mfma_f32_16x16x32_bf16 v[74:77], v[164:167], v[216:219], v[74:77]
	v_mfma_f32_16x16x32_bf16 v[126:129], v[160:163], v[192:195], v[126:129]
	v_mfma_f32_16x16x32_bf16 v[122:125], v[168:171], v[192:195], v[122:125]
	v_mfma_f32_16x16x32_bf16 v[110:113], v[160:163], v[200:203], v[110:113]
	v_mfma_f32_16x16x32_bf16 v[106:109], v[168:171], v[200:203], v[106:109]
	v_mfma_f32_16x16x32_bf16 v[94:97], v[160:163], v[212:215], v[94:97]
	v_mfma_f32_16x16x32_bf16 v[90:93], v[168:171], v[212:215], v[90:93]
	v_mfma_f32_16x16x32_bf16 v[78:81], v[160:163], v[220:223], v[78:81]
	v_mfma_f32_16x16x32_bf16 v[74:77], v[168:171], v[220:223], v[74:77]
	s_setprio 0
	s_setprio 1
	v_mfma_f32_16x16x32_bf16 v[118:121], v[172:175], v[188:191], v[118:121]
	v_mfma_f32_16x16x32_bf16 v[114:117], v[180:183], v[188:191], v[114:117]
	v_mfma_f32_16x16x32_bf16 v[102:105], v[172:175], v[196:199], v[102:105]
	v_mfma_f32_16x16x32_bf16 v[98:101], v[180:183], v[196:199], v[98:101]
	v_mfma_f32_16x16x32_bf16 v[86:89], v[172:175], v[208:211], v[86:89]
	v_mfma_f32_16x16x32_bf16 v[82:85], v[180:183], v[208:211], v[82:85]
	v_mfma_f32_16x16x32_bf16 v[70:73], v[172:175], v[216:219], v[70:73]
	v_mfma_f32_16x16x32_bf16 v[66:69], v[180:183], v[216:219], v[66:69]
	v_mfma_f32_16x16x32_bf16 v[118:121], v[176:179], v[192:195], v[118:121]
	v_mfma_f32_16x16x32_bf16 v[114:117], v[184:187], v[192:195], v[114:117]
	v_mfma_f32_16x16x32_bf16 v[102:105], v[176:179], v[200:203], v[102:105]
	v_mfma_f32_16x16x32_bf16 v[98:101], v[184:187], v[200:203], v[98:101]
	v_mfma_f32_16x16x32_bf16 v[86:89], v[176:179], v[212:215], v[86:89]
	v_mfma_f32_16x16x32_bf16 v[82:85], v[184:187], v[212:215], v[82:85]
	v_mfma_f32_16x16x32_bf16 v[70:73], v[176:179], v[220:223], v[70:73]
	v_mfma_f32_16x16x32_bf16 v[66:69], v[184:187], v[220:223], v[66:69]
	s_setprio 0
	s_barrier
	s_add_i32 s44, s72, s47
	s_mov_b32 m0, s44
	ds_read_b128 v[188:191], v154 offset:49152
	ds_read_b128 v[192:195], v154 offset:50176
	ds_read_b128 v[196:199], v154 offset:51200
	ds_read_b128 v[200:203], v154 offset:52224
	ds_read_b128 v[208:211], v154 offset:53248
	ds_read_b128 v[212:215], v154 offset:54272
	ds_read_b128 v[216:219], v154 offset:55296
	ds_read_b128 v[220:223], v154 offset:56320
	s_add_u32 s98, s40, s12
	s_addc_u32 s99, s41, s13
	global_load_lds_dwordx4 v132, s[98:99]
	s_add_i32 m0, s44, 0x2000
	s_add_u32 s40, s40, 0x40080
	v_lshl_add_u64 v[148:149], v[204:205], 0, s[12:13]
	s_addc_u32 s41, s41, 0
	s_add_i32 s44, s73, s47
	global_load_lds_dwordx4 v[148:149], off
	s_mov_b32 m0, s44
	s_nop 0
	global_load_lds_dwordx4 v132, s[40:41]
	s_add_i32 m0, s44, 0x2000
	s_nop 0
	global_load_lds_dwordx4 v136, s[40:41]
	s_waitcnt vmcnt(6)
	s_waitcnt lgkmcnt(0)
	s_barrier
	s_setprio 1
	s_waitcnt lgkmcnt(0)
	v_mfma_f32_16x16x32_bf16 v[62:65], v[156:159], v[188:191], v[62:65]
	v_mfma_f32_16x16x32_bf16 v[58:61], v[164:167], v[188:191], v[58:61]
	v_mfma_f32_16x16x32_bf16 v[46:49], v[156:159], v[196:199], v[46:49]
	v_mfma_f32_16x16x32_bf16 v[42:45], v[164:167], v[196:199], v[42:45]
	v_mfma_f32_16x16x32_bf16 v[30:33], v[156:159], v[208:211], v[30:33]
	v_mfma_f32_16x16x32_bf16 v[26:29], v[164:167], v[208:211], v[26:29]
	v_mfma_f32_16x16x32_bf16 v[14:17], v[156:159], v[216:219], v[14:17]
	v_mfma_f32_16x16x32_bf16 v[10:13], v[164:167], v[216:219], v[10:13]
	v_mfma_f32_16x16x32_bf16 v[62:65], v[160:163], v[192:195], v[62:65]
	v_mfma_f32_16x16x32_bf16 v[58:61], v[168:171], v[192:195], v[58:61]
	v_mfma_f32_16x16x32_bf16 v[46:49], v[160:163], v[200:203], v[46:49]
	v_mfma_f32_16x16x32_bf16 v[42:45], v[168:171], v[200:203], v[42:45]
	v_mfma_f32_16x16x32_bf16 v[30:33], v[160:163], v[212:215], v[30:33]
	v_mfma_f32_16x16x32_bf16 v[26:29], v[168:171], v[212:215], v[26:29]
	v_mfma_f32_16x16x32_bf16 v[14:17], v[160:163], v[220:223], v[14:17]
	v_mfma_f32_16x16x32_bf16 v[10:13], v[168:171], v[220:223], v[10:13]
	s_setprio 0
	s_setprio 1
	v_mfma_f32_16x16x32_bf16 v[54:57], v[172:175], v[188:191], v[54:57]
	v_mfma_f32_16x16x32_bf16 v[50:53], v[180:183], v[188:191], v[50:53]
	v_mfma_f32_16x16x32_bf16 v[38:41], v[172:175], v[196:199], v[38:41]
	v_mfma_f32_16x16x32_bf16 v[34:37], v[180:183], v[196:199], v[34:37]
	v_mfma_f32_16x16x32_bf16 v[22:25], v[172:175], v[208:211], v[22:25]
	v_mfma_f32_16x16x32_bf16 v[18:21], v[180:183], v[208:211], v[18:21]
	v_mfma_f32_16x16x32_bf16 v[6:9], v[172:175], v[216:219], v[6:9]
	v_mfma_f32_16x16x32_bf16 v[2:5], v[180:183], v[216:219], v[2:5]
	v_mfma_f32_16x16x32_bf16 v[54:57], v[176:179], v[192:195], v[54:57]
	v_mfma_f32_16x16x32_bf16 v[50:53], v[184:187], v[192:195], v[50:53]
	v_mfma_f32_16x16x32_bf16 v[38:41], v[176:179], v[200:203], v[38:41]
	v_mfma_f32_16x16x32_bf16 v[34:37], v[184:187], v[200:203], v[34:37]
	v_mfma_f32_16x16x32_bf16 v[22:25], v[176:179], v[212:215], v[22:25]
	v_mfma_f32_16x16x32_bf16 v[18:21], v[184:187], v[212:215], v[18:21]
	v_mfma_f32_16x16x32_bf16 v[6:9], v[176:179], v[220:223], v[6:9]
	v_mfma_f32_16x16x32_bf16 v[2:5], v[184:187], v[220:223], v[2:5]
	s_setprio 0
	s_add_i32 s71, s71, 2
	s_add_u32 s30, s30, 0x100
	s_addc_u32 s31, s31, 0
	s_add_u32 s33, s33, 0x100
	s_addc_u32 s70, s70, 0
	s_cmp_gt_u32 s71, 13
	s_barrier
	s_cbranch_scc0 .LBB0_740
	s_and_b64 vcc, exec, s[14:15]
	s_cbranch_vccz .LBB0_743
	s_barrier
